# baseline (speedup 1.0000x reference)
; DEVI void lds_barrier() { asm volatile("s_waitcnt lgkmcnt(0)" ::: "memory"); __builtin_amdgcn_s_barrier(); asm volatile("" ::: "memory"); }
; template <int MODE> ...
;     ...
;   for (int wg0 = vb; wg0 < nwg; wg0 += nvb) {
;     int wgid = wg0;
;     { int q = nwg / NXCD, r = nwg % NXCD, xcd = wgid % NXCD, off = wgid / NXCD;
;       wgid = (xcd < r ? xcd * (q + 1) : r * (q + 1) + (xcd - r) * q) + off; }
;     int nig = WGM * nN, gid = wgid / nig, fm = gid * WGM, gsz = min(nM - fm, WGM);
;     int pm = fm + ((wgid % nig) % gsz), pn = (wgid % nig) / gsz, brow = pm * BM, bcol = pn * BM;
;     ...
;         const float scale = (pn < 6) ? 0.08838834764831845f : 1.0f;
;         const int wbase = (ewr * 64 + efq * 4) * 1024 + (((ewc ^ efq) << 3) << 4) + (efr >> 2) * 16 + (efr & 3) * 4;
; #pragma unroll
;         for (int ai = 0; ai < 2; ++ai) {
;           if (ai) lds_barrier();
; #pragma unroll
;           for (int bj = 0; bj < 2; ++bj)
; #pragma unroll
;             for (int m = 0; m < 4; ++m)
; #pragma unroll
;               for (int n = 0; n < 2; ++n)
; #pragma unroll
;                 for (int j = 0; j < 4; ++j)
;                   *(float*)(ls + wbase + ((m * 16 + j) * 1024 + (bj * 32 + n * 4) * 16)) = acc[ai][bj][m][n][j];
;           lds_barrier();
.LBB0_157:
	s_or_b64 exec, exec, s[72:73]
	s_add_u32 s88, s82, s14
	s_cmp_lt_u32 s88, 0x680
	s_cbranch_scc0 .Lpf_m2_skip
	s_and_b32 s89, s88, 7
	s_lshr_b32 s90, s88, 3
	s_mul_i32 s89, s89, 0xd0
	s_add_u32 s89, s89, s90
	s_mul_hi_u32 s90, s89, 0x4ec4ec4f
	s_lshr_b32 s90, s90, 7
	s_mul_i32 s91, s90, 0x1a0
	s_sub_u32 s91, s89, s91
	s_and_b32 s92, s91, 7
	s_lshr_b32 s91, s91, 3
	s_lshl_b32 s90, s90, 3
	s_add_u32 s90, s90, s92
	v_readfirstlane_b32 s92, v164
	v_and_b32_e32 v244, 0xff, v164
	s_nop 1
	s_cmp_lt_u32 s92, 0x100
	s_cselect_b32 s96, s90, s91
	s_cselect_b32 s92, s56, s3
	s_cselect_b32 s93, s57, s15
	s_lshl_b32 s96, s96, 21
	s_add_u32 s92, s92, s96
	s_addc_u32 s93, s93, 0
	v_lshlrev_b32_e32 v244, 13, v244
	global_load_dword v243, v244, s[92:93]
	global_load_dword v245, v244, s[92:93] offset:128
.Lpf_m2_skip:
	v_mov_b32_e32 v170, v164
	s_mov_b64 s[72:73], -1
	v_bfe_u32 v128, v170, 6, 2
	v_bfe_u32 v173, v170, 4, 2
	v_ashrrev_i32_e32 v172, 8, v170
	v_and_b32_e32 v171, 15, v170
	s_cmpk_lt_i32 s83, 0x60
	v_xor_b32_e32 v174, v128, v173
	s_cbranch_scc0 .LBB0_163
	v_lshlrev_b32_e32 v128, 16, v172
	v_lshlrev_b32_e32 v139, 12, v173
	v_lshlrev_b32_e32 v140, 7, v174
	v_lshlrev_b32_e32 v141, 2, v171
	v_lshlrev_b32_e32 v142, 2, v170
	v_and_b32_e32 v141, 48, v141
	v_and_b32_e32 v142, 12, v142
	v_or3_b32 v128, v128, v139, v140
	v_or3_b32 v179, v128, v141, v142
	v_lshrrev_b32_e32 v128, 3, v170
	v_bfe_u32 v139, v170, 3, 1
	v_and_b32_e32 v180, 7, v170
	v_lshlrev_b32_e32 v140, 5, v139
	v_lshlrev_b32_e32 v141, 1, v180
	v_and_b32_e32 v128, 24, v128
	v_or_b32_e32 v142, v140, v141
	v_bitop3_b32 v140, v140, v128, v141 bitop3:0x36
	s_cmp_lt_i32 s83, 48
	v_lshlrev_b32_e32 v175, 4, v140
	v_bitop3_b32 v140, v142, v128, 1 bitop3:0x36
	s_cselect_b64 vcc, -1, 0
	v_lshlrev_b32_e32 v176, 4, v140
	v_bitop3_b32 v140, v142, v128, 16 bitop3:0x36
	v_bitop3_b32 v128, v142, v128, 17 bitop3:0x36
	s_lshl_b64 s[72:73], s[66:67], 1
	v_lshlrev_b32_e32 v178, 4, v128
	v_lshlrev_b32_e32 v128, 5, v180
	s_add_u32 s72, s33, s72
	v_lshlrev_b32_e32 v177, 4, v140
	v_lshl_add_u64 v[140:141], s[10:11], 0, v[128:129]
	v_lshl_add_u64 v[142:143], s[12:13], 0, v[128:129]
	s_addc_u32 s73, s34, s73
	v_lshlrev_b32_e32 v128, 8, v139
	v_lshl_add_u64 v[144:145], s[72:73], 0, v[128:129]
	v_lshlrev_b32_e32 v128, 4, v180
	v_lshl_add_u64 v[144:145], v[144:145], 0, v[128:129]
	v_add_u32_e32 v128, 0x400, v179
	v_add_u32_e32 v180, 0x800, v179
	v_add_u32_e32 v181, 0xc00, v179
	v_add_u32_e32 v182, 0x4000, v179
	v_add_u32_e32 v183, 0x4400, v179
	v_add_u32_e32 v184, 0x4800, v179
	v_add_u32_e32 v185, 0x4c00, v179
	v_add_u32_e32 v186, 0x8000, v179
	v_add_u32_e32 v187, 0x8400, v179
	v_add_u32_e32 v188, 0x8800, v179
	v_add_u32_e32 v189, 0x8c00, v179
	v_add_u32_e32 v190, 0xc000, v179
	v_add_u32_e32 v191, 0xc400, v179
	v_add_u32_e32 v192, 0xc800, v179
	v_add_u32_e32 v193, 0xcc00, v179
	ds_write2_b32 v179, v124, v120 offset1:16
	ds_write2_b32 v128, v125, v121 offset1:16
	ds_write2_b32 v180, v126, v122 offset1:16
	ds_write2_b32 v181, v127, v123 offset1:16
	ds_write2_b32 v182, v116, v112 offset1:16
	ds_write2_b32 v183, v117, v113 offset1:16
	ds_write2_b32 v184, v118, v114 offset1:16
	ds_write2_b32 v185, v119, v115 offset1:16
	ds_write2_b32 v186, v108, v104 offset1:16
	ds_write2_b32 v187, v109, v105 offset1:16
	ds_write2_b32 v188, v110, v106 offset1:16
	ds_write2_b32 v189, v111, v107 offset1:16
	ds_write2_b32 v190, v100, v96 offset1:16
	ds_write2_b32 v191, v101, v97 offset1:16
	ds_write2_b32 v192, v102, v98 offset1:16
	ds_write2_b32 v193, v103, v99 offset1:16
	ds_write2_b32 v179, v92, v88 offset0:128 offset1:144
	ds_write2_b32 v128, v93, v89 offset0:128 offset1:144
	ds_write2_b32 v180, v94, v90 offset0:128 offset1:144
	ds_write2_b32 v181, v95, v91 offset0:128 offset1:144
	ds_write2_b32 v182, v84, v80 offset0:128 offset1:144
	ds_write2_b32 v183, v85, v81 offset0:128 offset1:144
	ds_write2_b32 v184, v86, v82 offset0:128 offset1:144
	ds_write2_b32 v185, v87, v83 offset0:128 offset1:144
	ds_write2_b32 v186, v76, v72 offset0:128 offset1:144
	ds_write2_b32 v187, v77, v73 offset0:128 offset1:144
	ds_write2_b32 v188, v78, v74 offset0:128 offset1:144
	ds_write2_b32 v189, v79, v75 offset0:128 offset1:144
	ds_write2_b32 v190, v68, v60 offset0:128 offset1:144
	ds_write2_b32 v191, v69, v61 offset0:128 offset1:144
	ds_write2_b32 v192, v70, v62 offset0:128 offset1:144
	ds_write2_b32 v193, v71, v63 offset0:128 offset1:144
	s_waitcnt lgkmcnt(0)
	s_barrier
	v_cndmask_b32_e32 v138, 1.0, v169, vcc
	v_mov_b32_e32 v139, v138
	s_mov_b32 s69, 0

; DEVI u16 f2bf(float f) { return (u16)(pack2(f, 0.f) & 0xffffu); }
; DEVI float bf2f(u16 h) { return __uint_as_float(((unsigned)h) << 16); }
; DEVI void lds_barrier() { asm volatile("s_waitcnt lgkmcnt(0)" ::: "memory"); __builtin_amdgcn_s_barrier(); asm volatile("" ::: "memory"); }
; template <int MODE> ...
;     ...
;   for (int wg0 = vb; wg0 < nwg; wg0 += nvb) {
;     int wgid = wg0;
;     { int q = nwg / NXCD, r = nwg % NXCD, xcd = wgid % NXCD, off = wgid / NXCD;
;       wgid = (xcd < r ? xcd * (q + 1) : r * (q + 1) + (xcd - r) * q) + off; }
;     int nig = WGM * nN, gid = wgid / nig, fm = gid * WGM, gsz = min(nM - fm, WGM);
;     int pm = fm + ((wgid % nig) % gsz), pn = (wgid % nig) / gsz, brow = pm * BM, bcol = pn * BM;
;     ...
;         const int colt = ewc * 32 + efr;
;         const int colg = pn * 128 + colt;
;         float cw0[2], cw1[2], cw2[2], cbb[2];
; #pragma unroll
;         for (int n = 0; n < 2; ++n) {
;           cw0[n] = aux0[colg + n * 16]; cw1[n] = aux0[DFF + colg + n * 16]; cw2[n] = aux0[2 * DFF + colg + n * 16]; cbb[n] = aux1[colg + n * 16];
;         }
;         const int gbase = (ewr * 64 + efq * 4) * 256 + colt * 2;
; #pragma unroll
;         for (int ai = 0; ai < 2; ++ai)
; #pragma unroll
;           for (int m = 0; m < 4; ++m)
; #pragma unroll
;             for (int n = 0; n < 2; ++n) {
;               *(u16*)(ls + gbase + ((ai * HALF + m * 16 + 0) * 256 + n * 32)) = f2bf(acc[ai][0][m][n][0]);
;               *(u16*)(ls + gbase + ((ai * HALF + m * 16 + 3) * 256 + n * 32)) = f2bf(acc[ai][0][m][n][3]);
;             }
;         lds_barrier();
;         const int hbase = 65536 + (ewr * 64 + efq * 4) * 256 + (((ewc ^ efq) << 2) << 4) + (efr >> 3) * 16 + (efr & 7) * 2;
; #pragma unroll
;         for (int ai = 0; ai < 2; ++ai)
; #pragma unroll
;           for (int m = 0; m < 4; ++m)
; #pragma unroll
;             for (int n = 0; n < 2; ++n) {
;               const int rowb = ai * HALF + ewr * 64 + m * 16 + efq * 4;
;               float gm = rowb > 0 ? bf2f(*(const u16*)(ls + gbase + ((ai * HALF + m * 16 - 1) * 256 + n * 32))) : 0.f;
;               float gp = rowb < 252 ? bf2f(*(const u16*)(ls + gbase + ((ai * HALF + m * 16 + 4) * 256 + n * 32))) : 0.f;
;               float g0 = acc[ai][0][m][n][0], g1 = acc[ai][0][m][n][1], g2 = acc[ai][0][m][n][2], g3 = acc[ai][0][m][n][3];
.LBB0_594:
	s_or_b64 exec, exec, s[8:9]
	s_add_u32 s88, s85, s14
	s_cmp_lt_u32 s88, 0xac0
	s_cbranch_scc0 .Lpf_m3_skip
	s_and_b32 s89, s88, 7
	s_lshr_b32 s90, s88, 3
	s_mul_i32 s89, s89, 0x158
	s_add_u32 s89, s89, s90
	s_mul_hi_u32 s90, s89, 0x2fa0be83
	s_lshr_b32 s90, s90, 7
	s_mul_i32 s91, s90, 0x2b0
	s_sub_u32 s91, s89, s91
	s_and_b32 s92, s91, 7
	s_lshr_b32 s91, s91, 3
	s_lshl_b32 s90, s90, 3
	s_add_u32 s90, s90, s92
	v_readfirstlane_b32 s92, v164
	v_and_b32_e32 v244, 0xff, v164
	s_nop 1
	s_cmp_lt_u32 s92, 0x100
	s_cselect_b32 s96, s90, s91
	s_cselect_b32 s92, s56, s16
	s_cselect_b32 s93, s57, s17
	s_lshl_b32 s96, s96, 21
	s_add_u32 s92, s92, s96
	s_addc_u32 s93, s93, 0
	v_lshlrev_b32_e32 v244, 13, v244
	global_load_dword v243, v244, s[92:93]
	global_load_dword v245, v244, s[92:93] offset:128
.Lpf_m3_skip:
	v_mov_b32_e32 v140, v164
	s_lshl_b32 s66, s34, 7
	v_bfe_u32 v168, v140, 6, 2
	v_and_b32_e32 v128, 15, v140
	v_lshl_or_b32 v169, v168, 5, v128
	v_or_b32_e32 v138, s66, v169
	v_ashrrev_i32_e32 v139, 31, v138
	v_lshlrev_b64 v[130:131], 2, v[138:139]
	v_lshl_add_u64 v[132:133], s[24:25], 0, v[130:131]
	v_add_co_u32_e32 v142, vcc, 0xa000, v132
	v_lshl_add_u64 v[130:131], s[26:27], 0, v[130:131]
	s_nop 0
	v_addc_co_u32_e32 v143, vcc, 0, v133, vcc
	v_add_co_u32_e32 v144, vcc, 0x15000, v132
	v_ashrrev_i32_e32 v141, 8, v140
	s_nop 0
	v_addc_co_u32_e32 v145, vcc, 0, v133, vcc
	global_load_dword v171, v[132:133], off
	global_load_dword v172, v[142:143], off offset:3072
	global_load_dword v173, v[144:145], off offset:2048
	s_nop 0
	global_load_dword v144, v[144:145], off offset:2112
	s_nop 0
	global_load_dword v145, v[142:143], off offset:3136
	global_load_dword v167, v[132:133], off offset:64
	global_load_dword v170, v[130:131], off
	s_nop 0
	global_load_dword v143, v[130:131], off offset:64
	v_bfe_u32 v142, v140, 4, 2
	v_lshlrev_b32_e32 v130, 6, v141
	v_lshl_or_b32 v174, v142, 2, v130
	v_lshlrev_b32_e32 v175, 8, v174
	v_lshl_or_b32 v169, v169, 1, v175
	v_cvt_pk_bf16_f32 v130, v4, s0
	ds_write_b16 v169, v130
	v_cvt_pk_bf16_f32 v130, v7, s0
	ds_write_b16 v169, v130 offset:768
	v_cvt_pk_bf16_f32 v130, v0, s0
	ds_write_b16 v169, v130 offset:32
	v_cvt_pk_bf16_f32 v130, v3, s0
	ds_write_b16 v169, v130 offset:800
	v_cvt_pk_bf16_f32 v130, v124, s0
	ds_write_b16 v169, v130 offset:4096
	v_cvt_pk_bf16_f32 v130, v127, s0
	ds_write_b16 v169, v130 offset:4864
	v_cvt_pk_bf16_f32 v130, v116, s0
	ds_write_b16 v169, v130 offset:4128
	v_cvt_pk_bf16_f32 v130, v119, s0
	ds_write_b16 v169, v130 offset:4896
	v_cvt_pk_bf16_f32 v130, v108, s0
	ds_write_b16 v169, v130 offset:8192
	v_cvt_pk_bf16_f32 v130, v111, s0
	ds_write_b16 v169, v130 offset:8960
	v_cvt_pk_bf16_f32 v130, v100, s0
	ds_write_b16 v169, v130 offset:8224
	v_cvt_pk_bf16_f32 v130, v103, s0
	ds_write_b16 v169, v130 offset:8992
	v_cvt_pk_bf16_f32 v130, v92, s0
	ds_write_b16 v169, v130 offset:12288
	v_cvt_pk_bf16_f32 v130, v95, s0
	ds_write_b16 v169, v130 offset:13056
	v_cvt_pk_bf16_f32 v130, v84, s0
	ds_write_b16 v169, v130 offset:12320
	v_cvt_pk_bf16_f32 v130, v87, s0
	ds_write_b16 v169, v130 offset:13088
	v_cvt_pk_bf16_f32 v130, v76, s0
	ds_write_b16 v169, v130 offset:32768
	v_cvt_pk_bf16_f32 v130, v79, s0
	ds_write_b16 v169, v130 offset:33536
	v_cvt_pk_bf16_f32 v130, v68, s0
	ds_write_b16 v169, v130 offset:32800
	v_cvt_pk_bf16_f32 v130, v71, s0
	ds_write_b16 v169, v130 offset:33568
	v_cvt_pk_bf16_f32 v130, v60, s0
	ds_write_b16 v169, v130 offset:36864
	v_cvt_pk_bf16_f32 v130, v63, s0
	ds_write_b16 v169, v130 offset:37632
	v_cvt_pk_bf16_f32 v130, v52, s0
	ds_write_b16 v169, v130 offset:36896
	v_cvt_pk_bf16_f32 v130, v55, s0
	ds_write_b16 v169, v130 offset:37664
	v_cvt_pk_bf16_f32 v130, v44, s0
	ds_write_b16 v169, v130 offset:40960
	v_cvt_pk_bf16_f32 v130, v47, s0
	ds_write_b16 v169, v130 offset:41728
	v_cvt_pk_bf16_f32 v130, v36, s0
	ds_write_b16 v169, v130 offset:40992
	v_cvt_pk_bf16_f32 v130, v39, s0
	ds_write_b16 v169, v130 offset:41760
	v_cvt_pk_bf16_f32 v130, v20, s0
	ds_write_b16 v169, v130 offset:45056
	v_cvt_pk_bf16_f32 v130, v23, s0
	ds_write_b16 v169, v130 offset:45824
	v_cvt_pk_bf16_f32 v130, v16, s0
	ds_write_b16 v169, v130 offset:45088
	v_cvt_pk_bf16_f32 v130, v19, s0
	ds_write_b16 v169, v130 offset:45856
	s_waitcnt lgkmcnt(0)
	s_barrier
	v_cmp_lt_i32_e64 s[8:9], 0, v174
	v_mov_b32_e32 v176, 0
	v_mov_b32_e32 v177, 0
	s_and_saveexec_b64 s[10:11], s[8:9]
	s_cbranch_execz .LBB0_596
	v_add_u32_e32 v130, 0xffffff00, v169
	ds_read_u16 v130, v130
	s_waitcnt lgkmcnt(0)
	v_lshlrev_b32_e32 v177, 16, v130
